# LayerNorm row loops software-pipelined: next row's loads issued before the current row's reductions, counted vmcnt(8) instead of vmcnt(0)
# speedup vs baseline: 1.2815x; 1.0100x over previous
; DI int tid_() { int t = __builtin_amdgcn_workitem_id_x(); asm volatile("" : "+v"(t)); return t; }
; DI float wave_sum(float v) { for (int o = 32; o >= 1; o >>= 1) v += __shfl_xor(v, o); return v; }
; DI void ln_phase(float* x32, bf16_t* xb, const float* g, const float* b) {
;   const int lane = tid_() & 63, wv = tid_() >> 6;
;   float4 gg[4], bb[4];
; #pragma unroll
;   for (int j = 0; j < 4; ++j) { gg[j] = *(const float4*)(g + j * 256 + lane * 4); bb[j] = *(const float4*)(b + j * 256 + lane * 4); }
;   for (int row = blockIdx.x * 4 + wv; row < T_; row += gridDim.x * 4) {
;     f32x4 v[4];
; #pragma unroll
;     for (int j = 0; j < 4; ++j) v[j] = gldfv(x32 + (size_t)row * D_ + j * 256 + lane * 4);
;     asm volatile("s_waitcnt vmcnt(0)" : "+v"(v[0]), "+v"(v[1]), "+v"(v[2]), "+v"(v[3]) :: "memory");
;     float s = 0.f;
; #pragma unroll
;     for (int j = 0; j < 4; ++j) s += (v[j][0] + v[j][1]) + (v[j][2] + v[j][3]);
;     s = wave_sum(s); const float mu = s * (1.f / D_); float q = 0.f;
; DI void run_phase(const Params& p, int ph, char* smem) {
;     ...
;   const int l = (ph - 1) / 12, sp = (ph - 1) % 12;
;   const float alpha = 1.4142135623730951f;
;   bf16_t* xb = (bf16_t*)(p.ws + OFF_XB); bf16_t* big = (bf16_t*)(p.ws + OFF_BIG);
;   const bf16_t* wgu = (const bf16_t*)(p.ws + OFF_GU); const bf16_t* wdn = (const bf16_t*)(p.ws + OFF_DN);
;   EpiArgs e; e.obf = big; e.resid = p.out; e.of32 = p.out; e.alpha = alpha; e.sc = 0.5f; e.rope = (const float*)(p.ws + OFF_ROPE);
;   switch (sp) {
;     case 0: case 9: gemm_phase<0>(xb, D_, wgu, D_, 2 * DFF, smem, e); break;
;     case 1: if (l == 0) e.resid = p.x; gemm_phase<2>(big, DFF, wdn, DFF, D_, smem, e); break;
;     case 10: gemm_phase<2>(big, DFF, wdn, DFF, D_, smem, e); break;
;     case 2: ln_phase(p.out, xb, p.ln1g + l * D_, p.ln1b + l * D_); break;
;     case 3: gemm_phase<1>(xb, D_, (const bf16_t*)(p.ws + OFF_WIN), D_, LDP, smem, e); break;
;     case 4: m0_phase(p, l, smem); break;
;     case 5: m1_phase(p, l, smem); break;
;     case 6: m2_phase(p, l, smem); break;
;     case 7: e.sc = 1.f; gemm_phase<2>(xb, D_, (const bf16_t*)(p.ws + OFF_WOUT), D_, D_, smem, e); break;
;     case 8: ln_phase(p.out, xb, p.ln2g + l * D_, p.ln2b + l * D_); convert_weights(p, l, 2, smem); break;
;     case 11: ln_phase(p.out, xb, p.ln3g + l * D_, p.ln3b + l * D_); if (l + 1 < 2) convert_weights(p, l + 1, 1, smem); break;
.LBB0_11:
	v_readlane_b32 s36, v245, 4
	v_readlane_b32 s40, v245, 8
	s_add_i32 s0, s40, -1
	s_mul_hi_i32 s1, s0, 0x2aaaaaab
	s_lshr_b32 s2, s1, 31
	s_ashr_i32 s1, s1, 1
	s_add_i32 s4, s1, s2
	s_mov_b32 s2, s4
	s_mul_i32 s1, s4, 12
	v_writelane_b32 v242, s2, 20
	s_sub_i32 s0, s0, s1
	s_cmp_lt_i32 s0, 6
	v_writelane_b32 v242, s3, 21
	v_readlane_b32 s37, v245, 5
	v_readlane_b32 s38, v245, 6
	v_readlane_b32 s39, v245, 7
	v_readlane_b32 s41, v245, 9
	v_readlane_b32 s42, v245, 10
	v_readlane_b32 s43, v245, 11
	v_writelane_b32 v242, s0, 22
	s_cbranch_scc1 .LBB0_22
	s_cmp_gt_i32 s0, 8
	s_cbranch_scc0 .LBB0_23
	s_cmp_gt_i32 s0, 9
	s_mov_b64 s[0:1], -1
	s_cbranch_scc0 .LBB0_68
	v_readlane_b32 s0, v242, 22
	s_cmp_lt_i32 s0, 11
	s_mov_b64 s[0:1], -1
	s_cbranch_scc1 .LBB0_52
	v_readlane_b32 s0, v242, 22
	s_cmp_eq_u32 s0, 11
	s_cbranch_scc0 .LBB0_51
	v_mov_b32_e32 v0, v170
	v_mov_b32_e32 v1, v170
	v_readlane_b32 s0, v245, 60
	v_ashrrev_i32_e32 v1, 6, v1
	s_nop 0
	v_add_u32_e32 v32, s0, v1
	s_movk_i32 s0, 0x4000
	v_cmp_gt_i32_e32 vcc, s0, v32
	s_and_saveexec_b64 s[0:1], vcc
	v_readlane_b32 s8, v245, 61
	v_readlane_b32 s9, v245, 62
	s_mov_b64 s[12:13], 0x400
	s_mov_b64 s[20:21], 0x800
	s_mov_b64 s[22:23], 0xc00
	s_mov_b32 s11, 0x800000
	s_movk_i32 s24, 0x3fff
	s_cbranch_execz .LBB0_19
	v_readlane_b32 s4, v242, 20
	v_readlane_b32 s5, v242, 21
	s_lshl_b32 s4, s4, 10
	s_ashr_i32 s5, s4, 31
	v_readlane_b32 s36, v245, 20
	s_lshl_b64 s[4:5], s[4:5], 2
	v_readlane_b32 s42, v245, 26
	v_readlane_b32 s43, v245, 27
	s_add_u32 s6, s42, s4
	v_lshlrev_b32_e32 v0, 2, v0
	v_readlane_b32 s44, v245, 28
	s_addc_u32 s7, s43, s5
	v_and_b32_e32 v33, 0xfc, v0
	v_readlane_b32 s45, v245, 29
	s_add_u32 s4, s44, s4
	v_lshlrev_b32_e32 v142, 2, v33
	s_addc_u32 s5, s45, s5
	global_load_dwordx4 v[0:3], v142, s[6:7]
	global_load_dwordx4 v[4:7], v142, s[6:7] offset:1024
	global_load_dwordx4 v[8:11], v142, s[4:5]
	global_load_dwordx4 v[12:15], v142, s[4:5] offset:1024
	global_load_dwordx4 v[16:19], v142, s[6:7] offset:2048
	global_load_dwordx4 v[20:23], v142, s[6:7] offset:3072
	global_load_dwordx4 v[24:27], v142, s[4:5] offset:2048
	global_load_dwordx4 v[28:31], v142, s[4:5] offset:3072
	v_readlane_b32 s37, v245, 21
	v_readlane_b32 s38, v245, 22
	v_readlane_b32 s39, v245, 23
	v_readlane_b32 s40, v245, 24
	v_readlane_b32 s41, v245, 25
	v_readlane_b32 s36, v245, 4
	v_readlane_b32 s37, v245, 5
	v_readlane_b32 s4, v245, 52
	v_readlane_b32 s5, v245, 53
	v_lshl_add_u64 v[34:35], s[36:37], 0, v[142:143]
	v_lshlrev_b32_e32 v142, 1, v33
	v_lshl_add_u64 v[36:37], s[4:5], 0, v[142:143]
	s_mov_b64 s[4:5], 0
	v_readlane_b32 s46, v245, 30
	v_readlane_b32 s47, v245, 31
	v_readlane_b32 s48, v245, 32
	v_readlane_b32 s49, v245, 33
	v_readlane_b32 s50, v245, 34
	v_readlane_b32 s51, v245, 35
	v_readlane_b32 s38, v245, 6
	v_readlane_b32 s39, v245, 7
	v_readlane_b32 s40, v245, 8
	v_readlane_b32 s41, v245, 9
	v_readlane_b32 s42, v245, 10
	v_readlane_b32 s43, v245, 11
	v_mov_b32_e32 v118, v32
	v_ashrrev_i32_e32 v119, 31, v32
	v_lshlrev_b64 v[116:117], 12, v[118:119]
	v_lshl_add_u64 v[116:117], v[34:35], 0, v[116:117]
	global_load_dwordx4 v[38:41], v[116:117], off
	global_load_dwordx4 v[42:45], v[116:117], off offset:1024
	global_load_dwordx4 v[46:49], v[116:117], off offset:2048
	global_load_dwordx4 v[50:53], v[116:117], off offset:3072
	s_waitcnt vmcnt(0)
.LBB0_18:
	s_waitcnt vmcnt(8)
	v_mov_b32_e32 v100, v38
	v_mov_b32_e32 v101, v39
	v_mov_b32_e32 v102, v40
	v_mov_b32_e32 v103, v41
	v_mov_b32_e32 v104, v42
	v_mov_b32_e32 v105, v43
	v_mov_b32_e32 v106, v44
	v_mov_b32_e32 v107, v45
	v_mov_b32_e32 v108, v46
	v_mov_b32_e32 v109, v47
	v_mov_b32_e32 v110, v48
	v_mov_b32_e32 v111, v49
	v_mov_b32_e32 v112, v50
	v_mov_b32_e32 v113, v51
	v_mov_b32_e32 v114, v52
	v_mov_b32_e32 v115, v53
	v_ashrrev_i32_e32 v33, 31, v32
	v_lshlrev_b64 v[116:117], 12, v[32:33]
	v_lshl_add_u64 v[54:55], v[34:35], 0, v[116:117]
	s_load_dword s2, s[8:9], 0x0
	s_waitcnt lgkmcnt(0)
	v_lshl_add_u32 v118, s2, 2, v32
	v_cmp_lt_i32_e32 vcc, s24, v118
	s_nop 1
	v_cndmask_b32_e32 v118, v118, v32, vcc
	v_ashrrev_i32_e32 v119, 31, v118
	v_lshlrev_b64 v[116:117], 12, v[118:119]
	v_lshl_add_u64 v[116:117], v[34:35], 0, v[116:117]
	global_load_dwordx4 v[38:41], v[116:117], off
	global_load_dwordx4 v[42:45], v[116:117], off offset:1024
	global_load_dwordx4 v[46:49], v[116:117], off offset:2048
	global_load_dwordx4 v[50:53], v[116:117], off offset:3072
	v_cmp_lt_i32_e32 vcc, v180, v179
	s_nop 0
	v_mov_b32_e32 v56, v101
	v_mov_b32_e32 v57, v102
	v_mov_b32_e32 v58, v100
	v_mov_b32_e32 v59, v103
	v_pk_add_f32 v[56:57], v[56:57], v[58:59]
	v_mov_b32_e32 v58, v105
	v_mov_b32_e32 v59, v106
	v_mov_b32_e32 v60, v104
	v_mov_b32_e32 v61, v107
	v_pk_add_f32 v[58:59], v[58:59], v[60:61]
	v_add_f32_e32 v56, v56, v57
	v_pk_add_f32 v[58:59], v[58:59], v[58:59] op_sel_hi:[0,1]
	v_add_f32_e32 v57, 0, v56
	v_add_f32_e32 v61, v108, v109
	v_add_f32_e32 v63, v110, v111
	v_mov_b32_e32 v60, v112
	v_mov_b32_e32 v62, v113
	v_mov_b32_e32 v58, v114
	v_mov_b32_e32 v56, v115
	v_pk_add_f32 v[60:61], v[60:61], v[62:63]
	v_pk_add_f32 v[56:57], v[58:59], v[56:57]
	s_nop 0
	v_pk_add_f32 v[56:57], v[60:61], v[56:57]
	s_nop 0
	v_add_f32_e32 v56, v56, v57
	v_cndmask_b32_e32 v57, v177, v180, vcc
	v_lshlrev_b32_e32 v62, 2, v57
	ds_bpermute_b32 v57, v62, v56
	v_cmp_lt_i32_e32 vcc, v181, v179
	s_waitcnt lgkmcnt(0)
	v_add_f32_e32 v56, v56, v57
	v_cndmask_b32_e32 v57, v177, v181, vcc
	v_lshlrev_b32_e32 v63, 2, v57
	ds_bpermute_b32 v57, v63, v56
	v_cmp_lt_i32_e32 vcc, v182, v179
	s_waitcnt lgkmcnt(0)
	v_add_f32_e32 v56, v56, v57
	v_cndmask_b32_e32 v57, v177, v182, vcc
	v_lshlrev_b32_e32 v64, 2, v57
	ds_bpermute_b32 v57, v64, v56
	v_cmp_lt_i32_e32 vcc, v183, v179
	s_waitcnt lgkmcnt(0)
; DI float wave_sum(float v) { for (int o = 32; o >= 1; o >>= 1) v += __shfl_xor(v, o); return v; }
; DI void ln_phase(float* x32, bf16_t* xb, const float* g, const float* b) {
;     ...
;     s = wave_sum(s); const float mu = s * (1.f / D_); float q = 0.f;
; #pragma unroll
;     for (int j = 0; j < 4; ++j) { v[j] -= mu; q += v[j][0] * v[j][0] + v[j][1] * v[j][1] + v[j][2] * v[j][2] + v[j][3] * v[j][3]; }
;     q = wave_sum(q); const float rs = rsqrtf(q * (1.f / D_) + 1e-5f);
	v_add_f32_e32 v56, v56, v57
	v_cndmask_b32_e32 v57, v177, v183, vcc
	v_lshlrev_b32_e32 v65, 2, v57
	ds_bpermute_b32 v57, v65, v56
	v_cmp_lt_i32_e32 vcc, v184, v179
	s_waitcnt lgkmcnt(0)
	v_add_f32_e32 v56, v56, v57
	v_cndmask_b32_e32 v57, v177, v184, vcc
	v_lshlrev_b32_e32 v66, 2, v57
	ds_bpermute_b32 v57, v66, v56
	v_cmp_lt_i32_e32 vcc, v185, v179
	s_waitcnt lgkmcnt(0)
	v_add_f32_e32 v56, v56, v57
	v_cndmask_b32_e32 v57, v177, v185, vcc
	v_lshlrev_b32_e32 v67, 2, v57
	ds_bpermute_b32 v57, v67, v56
	s_waitcnt lgkmcnt(0)
	v_add_f32_e32 v60, v56, v57
	v_fmamk_f32 v101, v60, 0xba800000, v101
	v_fmamk_f32 v105, v60, 0xba800000, v105
	v_fmac_f32_e32 v100, 0xba800000, v60
	v_fmac_f32_e32 v104, 0xba800000, v60
	v_mov_b32_e32 v58, v101
	v_mov_b32_e32 v59, v105
	v_fmamk_f32 v102, v60, 0xba800000, v102
	v_fmamk_f32 v106, v60, 0xba800000, v106
	v_mov_b32_e32 v56, v100
	v_mov_b32_e32 v57, v104
	v_pk_mul_f32 v[58:59], v[58:59], v[58:59]
	v_fmamk_f32 v103, v60, 0xba800000, v103
	v_fmamk_f32 v107, v60, 0xba800000, v107
	v_pk_fma_f32 v[56:57], v[56:57], v[56:57], v[58:59]
	v_mov_b32_e32 v58, v102
	v_mov_b32_e32 v59, v106
	v_fmamk_f32 v109, v60, 0xba800000, v109
	v_fmamk_f32 v113, v60, 0xba800000, v113
	v_pk_fma_f32 v[56:57], v[58:59], v[58:59], v[56:57]
	v_mov_b32_e32 v58, v103
	v_mov_b32_e32 v59, v107
	v_fmamk_f32 v111, v60, 0xba800000, v111
	v_fmamk_f32 v110, v60, 0xba800000, v110
	v_fmac_f32_e32 v108, 0xba800000, v60
	v_fmamk_f32 v115, v60, 0xba800000, v115
	v_fmamk_f32 v114, v60, 0xba800000, v114
	v_fmac_f32_e32 v112, 0xba800000, v60
	v_mov_b32_e32 v60, v113
	v_mov_b32_e32 v61, v109
	v_pk_fma_f32 v[56:57], v[58:59], v[58:59], v[56:57]
	v_mov_b32_e32 v58, v112
	v_mov_b32_e32 v59, v108
	v_pk_mul_f32 v[60:61], v[60:61], v[60:61]
	v_add_f32_e32 v56, v56, v57
	v_pk_fma_f32 v[58:59], v[58:59], v[58:59], v[60:61]
	v_mov_b32_e32 v60, v114
	v_mov_b32_e32 v61, v110
	v_pk_fma_f32 v[58:59], v[60:61], v[60:61], v[58:59]
	v_mov_b32_e32 v60, v115
	v_mov_b32_e32 v61, v111
	v_pk_fma_f32 v[58:59], v[60:61], v[60:61], v[58:59]
	s_nop 0
	v_add_f32_e32 v56, v59, v56
	v_add_f32_e32 v56, v58, v56
	ds_bpermute_b32 v57, v62, v56
	v_lshlrev_b64 v[58:59], 11, v[32:33]
	v_lshl_add_u64 v[58:59], v[36:37], 0, v[58:59]
	s_waitcnt lgkmcnt(0)
	v_add_f32_e32 v56, v56, v57
	ds_bpermute_b32 v57, v63, v56
	s_waitcnt lgkmcnt(0)
	v_add_f32_e32 v56, v56, v57
	ds_bpermute_b32 v57, v64, v56
	s_waitcnt lgkmcnt(0)
	v_add_f32_e32 v56, v56, v57
	ds_bpermute_b32 v57, v65, v56
	s_waitcnt lgkmcnt(0)
	v_add_f32_e32 v56, v56, v57
	ds_bpermute_b32 v57, v66, v56
	s_waitcnt lgkmcnt(0)
	v_add_f32_e32 v56, v56, v57
	ds_bpermute_b32 v57, v67, v56
	s_waitcnt lgkmcnt(0)
; DI unsigned pack2(float a, float b) { return (unsigned)f2bf(a) | ((unsigned)f2bf(b) << 16); }
; DI float wave_sum(float v) { for (int o = 32; o >= 1; o >>= 1) v += __shfl_xor(v, o); return v; }
; DI void ln_phase(float* x32, bf16_t* xb, const float* g, const float* b) {
;     ...
;     q = wave_sum(q); const float rs = rsqrtf(q * (1.f / D_) + 1e-5f);
; #pragma unroll
;     for (int j = 0; j < 4; ++j) {
;       const int c = j * 256 + lane * 4;
;       float4 y; y.x = v[j][0] * rs * gg[j].x + bb[j].x; y.y = v[j][1] * rs * gg[j].y + bb[j].y; y.z = v[j][2] * rs * gg[j].z + bb[j].z; y.w = v[j][3] * rs * gg[j].w + bb[j].w;
;       *(float4*)(x32 + (size_t)row * D_ + c) = y;
;       uint2 pk; pk.x = pack2(y.x, y.y); pk.y = pack2(y.z, y.w); *(uint2*)(xb + (size_t)row * D_ + c) = pk;
;     }
;   }
; DI void run_phase(const Params& p, int ph, char* smem) {
;     ...
;     case 11: ln_phase(p.out, xb, p.ln3g + l * D_, p.ln3b + l * D_); if (l + 1 < 2) convert_weights(p, l + 1, 1, smem); break;
	v_add_f32_e32 v56, v56, v57
	v_fmamk_f32 v56, v56, 0x3a800000, v171
	v_mul_f32_e32 v57, 0x4b800000, v56
	v_cmp_gt_f32_e32 vcc, s11, v56
	s_nop 1
	v_cndmask_b32_e32 v56, v56, v57, vcc
	v_rsq_f32_e32 v56, v56
	s_nop 0
	v_mul_f32_e32 v57, 0x45800000, v56
	v_cndmask_b32_e32 v56, v56, v57, vcc
	v_pk_mul_f32 v[100:101], v[100:101], v[56:57] op_sel_hi:[1,0]
	v_pk_mul_f32 v[102:103], v[102:103], v[56:57] op_sel_hi:[1,0]
	v_pk_fma_f32 v[100:101], v[0:1], v[100:101], v[8:9]
	v_pk_fma_f32 v[102:103], v[2:3], v[102:103], v[10:11]
	v_and_b32_sdwa v57, v100, v141 dst_sel:DWORD dst_unused:UNUSED_PAD src0_sel:WORD_1 src1_sel:DWORD
	v_and_b32_sdwa v33, v102, v141 dst_sel:DWORD dst_unused:UNUSED_PAD src0_sel:WORD_1 src1_sel:DWORD
	global_store_dwordx4 v[54:55], v[100:103], off
	v_add3_u32 v33, v102, v33, s17
	s_nop 0
	v_add3_u32 v100, v100, v57, s17
	v_and_b32_sdwa v102, v103, v141 dst_sel:DWORD dst_unused:UNUSED_PAD src0_sel:WORD_1 src1_sel:DWORD
	v_and_b32_sdwa v57, v101, v141 dst_sel:DWORD dst_unused:UNUSED_PAD src0_sel:WORD_1 src1_sel:DWORD
	v_add3_u32 v102, v103, v102, s17
	v_add3_u32 v101, v101, v57, s17
	v_and_b32_e32 v102, 0xffff0000, v102
	v_and_b32_e32 v103, 0xffff0000, v101
	v_or_b32_sdwa v101, v102, v33 dst_sel:DWORD dst_unused:UNUSED_PAD src0_sel:DWORD src1_sel:WORD_1
	v_or_b32_sdwa v100, v103, v100 dst_sel:DWORD dst_unused:UNUSED_PAD src0_sel:DWORD src1_sel:WORD_1
	global_store_dwordx2 v[58:59], v[100:101], off
	v_pk_mul_f32 v[100:101], v[104:105], v[56:57] op_sel_hi:[1,0]
	v_pk_mul_f32 v[102:103], v[106:107], v[56:57] op_sel_hi:[1,0]
	v_pk_fma_f32 v[100:101], v[4:5], v[100:101], v[12:13]
	v_pk_fma_f32 v[102:103], v[6:7], v[102:103], v[14:15]
	v_and_b32_sdwa v104, v100, v141 dst_sel:DWORD dst_unused:UNUSED_PAD src0_sel:WORD_1 src1_sel:DWORD
	v_and_b32_sdwa v33, v102, v141 dst_sel:DWORD dst_unused:UNUSED_PAD src0_sel:WORD_1 src1_sel:DWORD
	global_store_dwordx4 v[54:55], v[100:103], off offset:1024
	v_add3_u32 v33, v102, v33, s17
	s_nop 0
	v_add3_u32 v100, v100, v104, s17
	v_and_b32_sdwa v102, v103, v141 dst_sel:DWORD dst_unused:UNUSED_PAD src0_sel:WORD_1 src1_sel:DWORD
	v_and_b32_sdwa v104, v101, v141 dst_sel:DWORD dst_unused:UNUSED_PAD src0_sel:WORD_1 src1_sel:DWORD
	v_add3_u32 v102, v103, v102, s17
	v_add3_u32 v101, v101, v104, s17
	v_and_b32_e32 v102, 0xffff0000, v102
	v_and_b32_e32 v103, 0xffff0000, v101
	v_or_b32_sdwa v101, v102, v33 dst_sel:DWORD dst_unused:UNUSED_PAD src0_sel:DWORD src1_sel:WORD_1
	v_or_b32_sdwa v100, v103, v100 dst_sel:DWORD dst_unused:UNUSED_PAD src0_sel:DWORD src1_sel:WORD_1
	global_store_dwordx2 v[58:59], v[100:101], off offset:512
	v_pk_mul_f32 v[100:101], v[108:109], v[56:57] op_sel_hi:[1,0]
	v_pk_mul_f32 v[102:103], v[110:111], v[56:57] op_sel_hi:[1,0]
	v_pk_fma_f32 v[100:101], v[16:17], v[100:101], v[24:25]
	v_pk_fma_f32 v[102:103], v[18:19], v[102:103], v[26:27]
	v_and_b32_sdwa v104, v100, v141 dst_sel:DWORD dst_unused:UNUSED_PAD src0_sel:WORD_1 src1_sel:DWORD
	v_and_b32_sdwa v33, v102, v141 dst_sel:DWORD dst_unused:UNUSED_PAD src0_sel:WORD_1 src1_sel:DWORD
	global_store_dwordx4 v[54:55], v[100:103], off offset:2048
	v_add3_u32 v33, v102, v33, s17
	s_nop 0
	v_add3_u32 v100, v100, v104, s17
	v_and_b32_sdwa v102, v103, v141 dst_sel:DWORD dst_unused:UNUSED_PAD src0_sel:WORD_1 src1_sel:DWORD
	v_and_b32_sdwa v104, v101, v141 dst_sel:DWORD dst_unused:UNUSED_PAD src0_sel:WORD_1 src1_sel:DWORD
	v_add3_u32 v102, v103, v102, s17
	v_add3_u32 v101, v101, v104, s17
	v_and_b32_e32 v102, 0xffff0000, v102
	v_and_b32_e32 v103, 0xffff0000, v101
	v_or_b32_sdwa v101, v102, v33 dst_sel:DWORD dst_unused:UNUSED_PAD src0_sel:DWORD src1_sel:WORD_1
	v_or_b32_sdwa v100, v103, v100 dst_sel:DWORD dst_unused:UNUSED_PAD src0_sel:DWORD src1_sel:WORD_1
	global_store_dwordx2 v[58:59], v[100:101], off offset:1024
	v_pk_mul_f32 v[100:101], v[112:113], v[56:57] op_sel_hi:[1,0]
	v_pk_mul_f32 v[102:103], v[114:115], v[56:57] op_sel_hi:[1,0]
	v_pk_fma_f32 v[100:101], v[20:21], v[100:101], v[28:29]
	v_pk_fma_f32 v[102:103], v[22:23], v[102:103], v[30:31]
	v_and_b32_sdwa v104, v100, v141 dst_sel:DWORD dst_unused:UNUSED_PAD src0_sel:WORD_1 src1_sel:DWORD
	v_and_b32_sdwa v33, v102, v141 dst_sel:DWORD dst_unused:UNUSED_PAD src0_sel:WORD_1 src1_sel:DWORD
	global_store_dwordx4 v[54:55], v[100:103], off offset:3072
	v_add3_u32 v33, v102, v33, s17
	s_nop 0
	v_add3_u32 v100, v100, v104, s17
	v_and_b32_sdwa v102, v103, v141 dst_sel:DWORD dst_unused:UNUSED_PAD src0_sel:WORD_1 src1_sel:DWORD
	v_and_b32_sdwa v104, v101, v141 dst_sel:DWORD dst_unused:UNUSED_PAD src0_sel:WORD_1 src1_sel:DWORD
	v_add3_u32 v102, v103, v102, s17
	v_add3_u32 v101, v101, v104, s17
	v_and_b32_e32 v102, 0xffff0000, v102
	v_and_b32_e32 v103, 0xffff0000, v101
	v_or_b32_sdwa v101, v102, v33 dst_sel:DWORD dst_unused:UNUSED_PAD src0_sel:DWORD src1_sel:WORD_1
	v_or_b32_sdwa v100, v103, v100 dst_sel:DWORD dst_unused:UNUSED_PAD src0_sel:DWORD src1_sel:WORD_1
	global_store_dwordx2 v[58:59], v[100:101], off offset:1536
	s_load_dword s2, s[8:9], 0x0
	s_waitcnt lgkmcnt(0)
	v_lshl_add_u32 v32, s2, 2, v32
	v_cmp_lt_i32_e32 vcc, s24, v32
	s_or_b64 s[4:5], vcc, s[4:5]
	s_andn2_b64 exec, exec, s[4:5]
	s_cbranch_execnz .LBB0_18
.LBB0_19:
	s_or_b64 exec, exec, s[0:1]
	s_waitcnt vmcnt(0)
	v_readlane_b32 s36, v245, 4
	v_readlane_b32 s40, v245, 8
	s_cmp_gt_i32 s40, 12
	v_readlane_b32 s37, v245, 5
	v_readlane_b32 s38, v245, 6
	v_readlane_b32 s39, v245, 7
	v_readlane_b32 s41, v245, 9
	v_readlane_b32 s42, v245, 10
	v_readlane_b32 s43, v245, 11
	s_cbranch_scc1 .LBB0_51
	v_readlane_b32 s0, v245, 63
	v_readlane_b32 s1, v244, 0
	s_andn2_b64 vcc, exec, s[0:1]
	s_cbranch_vccnz .LBB0_51
	v_readlane_b32 s0, v242, 20
	s_add_i32 s6, s0, 1
	v_readlane_b32 s36, v243, 59
	v_readlane_b32 s1, v242, 21
	s_ashr_i32 s7, s6, 31
	s_mul_i32 s0, s6, 0x1600000
	v_readlane_b32 s42, v242, 1
	s_mul_hi_i32 s1, s6, 0x1600000
	v_readlane_b32 s43, v242, 2
	s_add_u32 s0, s42, s0
	v_readlane_b32 s44, v242, 3
	s_addc_u32 s1, s43, s1
	s_mul_i32 s4, s6, 0xb00000
	v_readlane_b32 s45, v242, 4
	s_mul_hi_i32 s2, s6, 0xb00000
	s_add_u32 s4, s44, s4
	v_readlane_b32 s40, v243, 63
	s_addc_u32 s5, s45, s2
	s_lshl_b64 s[8:9], s[6:7], 22
	v_readlane_b32 s41, v242, 0
	s_mul_hi_i32 s2, s6, 0xc94000
	s_mul_i32 s11, s6, 0xc94000
	s_add_u32 s6, s40, s8
	v_readlane_b32 s38, v243, 61
	s_addc_u32 s7, s41, s9
	v_readlane_b32 s39, v243, 62
	s_add_u32 s8, s38, s11
	v_readlane_b32 s12, v242, 15
	s_addc_u32 s9, s39, s2
	s_mov_b32 s2, s12
	v_readlane_b32 s37, v243, 60
	v_readlane_b32 s46, v242, 5
	v_readlane_b32 s47, v242, 6
	v_readlane_b32 s48, v242, 7
	v_readlane_b32 s49, v242, 8
	v_readlane_b32 s50, v242, 9
	v_readlane_b32 s51, v242, 10
	v_readlane_b32 s13, v242, 16
	s_branch .LBB0_25

; DI int tid_() { int t = __builtin_amdgcn_workitem_id_x(); asm volatile("" : "+v"(t)); return t; }
; DI float wave_sum(float v) { for (int o = 32; o >= 1; o >>= 1) v += __shfl_xor(v, o); return v; }
; DI f32x4 gldfv(const void* p) { f32x4 r; asm volatile("global_load_dwordx4 %0, %1, off" : "=v"(r) : "v"(p) : "memory"); return r; }
; DI void ln_phase(float* x32, bf16_t* xb, const float* g, const float* b) {
;   const int lane = tid_() & 63, wv = tid_() >> 6;
;   float4 gg[4], bb[4];
; #pragma unroll
;   for (int j = 0; j < 4; ++j) { gg[j] = *(const float4*)(g + j * 256 + lane * 4); bb[j] = *(const float4*)(b + j * 256 + lane * 4); }
;   for (int row = blockIdx.x * 4 + wv; row < T_; row += gridDim.x * 4) {
;     f32x4 v[4];
; #pragma unroll
;     for (int j = 0; j < 4; ++j) v[j] = gldfv(x32 + (size_t)row * D_ + j * 256 + lane * 4);
;     asm volatile("s_waitcnt vmcnt(0)" : "+v"(v[0]), "+v"(v[1]), "+v"(v[2]), "+v"(v[3]) :: "memory");
;     float s = 0.f;
; #pragma unroll
;     for (int j = 0; j < 4; ++j) s += (v[j][0] + v[j][1]) + (v[j][2] + v[j][3]);
;     s = wave_sum(s); const float mu = s * (1.f / D_); float q = 0.f;
; DI void run_phase(const Params& p, int ph, char* smem) {
;     ...
;   switch (sp) {
;     case 0: case 9: gemm_phase<0>(xb, D_, wgu, D_, 2 * DFF, smem, e); break;
;     case 1: if (l == 0) e.resid = p.x; gemm_phase<2>(big, DFF, wdn, DFF, D_, smem, e); break;
;     case 10: gemm_phase<2>(big, DFF, wdn, DFF, D_, smem, e); break;
;     case 2: ln_phase(p.out, xb, p.ln1g + l * D_, p.ln1b + l * D_); break;
;     case 3: gemm_phase<1>(xb, D_, (const bf16_t*)(p.ws + OFF_WIN), D_, LDP, smem, e); break;
;     case 4: m0_phase(p, l, smem); break;
;     case 5: m1_phase(p, l, smem); break;
;     case 6: m2_phase(p, l, smem); break;
;     case 7: e.sc = 1.f; gemm_phase<2>(xb, D_, (const bf16_t*)(p.ws + OFF_WOUT), D_, D_, smem, e); break;
;     case 8: ln_phase(p.out, xb, p.ln2g + l * D_, p.ln2b + l * D_); convert_weights(p, l, 2, smem); break;
.LBB0_69:
	v_readlane_b32 s0, v242, 22
	s_cmp_lt_i32 s0, 7
	s_mov_b64 s[0:1], -1
	s_cbranch_scc1 .LBB0_98
	v_readlane_b32 s0, v242, 22
	s_cmp_gt_i32 s0, 7
	s_mov_b64 s[0:1], -1
	s_cbranch_scc0 .LBB0_82
	v_mov_b32_e32 v0, v170
	v_mov_b32_e32 v1, v170
	v_readlane_b32 s0, v245, 60
	v_ashrrev_i32_e32 v1, 6, v1
	s_nop 0
	v_add_u32_e32 v32, s0, v1
	s_movk_i32 s0, 0x4000
	v_cmp_gt_i32_e32 vcc, s0, v32
	s_and_saveexec_b64 s[0:1], vcc
	v_readlane_b32 s8, v245, 61
	v_readlane_b32 s9, v245, 62
	s_mov_b64 s[12:13], 0x400
	s_mov_b64 s[20:21], 0x800
	s_mov_b64 s[22:23], 0xc00
	s_mov_b32 s11, 0x800000
	s_movk_i32 s24, 0x3fff
	s_cbranch_execz .LBB0_74
	v_readlane_b32 s4, v242, 20
	v_readlane_b32 s5, v242, 21
	s_lshl_b32 s4, s4, 10
	s_ashr_i32 s5, s4, 31
	v_readlane_b32 s36, v245, 20
	s_lshl_b64 s[4:5], s[4:5], 2
	v_readlane_b32 s38, v245, 22
	v_readlane_b32 s39, v245, 23
	s_add_u32 s6, s38, s4
	v_lshlrev_b32_e32 v0, 2, v0
	v_readlane_b32 s40, v245, 24
	s_addc_u32 s7, s39, s5
	v_and_b32_e32 v33, 0xfc, v0
	v_readlane_b32 s41, v245, 25
	s_add_u32 s4, s40, s4
	v_lshlrev_b32_e32 v142, 2, v33
	s_addc_u32 s5, s41, s5
	global_load_dwordx4 v[0:3], v142, s[6:7]
	global_load_dwordx4 v[4:7], v142, s[6:7] offset:1024
	global_load_dwordx4 v[8:11], v142, s[4:5]
	global_load_dwordx4 v[12:15], v142, s[4:5] offset:1024
	global_load_dwordx4 v[16:19], v142, s[6:7] offset:2048
	global_load_dwordx4 v[20:23], v142, s[6:7] offset:3072
	global_load_dwordx4 v[24:27], v142, s[4:5] offset:2048
	global_load_dwordx4 v[28:31], v142, s[4:5] offset:3072
	v_readlane_b32 s37, v245, 21
	v_readlane_b32 s42, v245, 26
	v_readlane_b32 s43, v245, 27
	v_readlane_b32 s36, v245, 4
	v_readlane_b32 s37, v245, 5
	v_readlane_b32 s4, v245, 52
	v_readlane_b32 s5, v245, 53
	v_lshl_add_u64 v[34:35], s[36:37], 0, v[142:143]
	v_lshlrev_b32_e32 v142, 1, v33
	v_lshl_add_u64 v[36:37], s[4:5], 0, v[142:143]
	s_mov_b64 s[4:5], 0
	v_readlane_b32 s44, v245, 28
	v_readlane_b32 s45, v245, 29
	v_readlane_b32 s46, v245, 30
	v_readlane_b32 s47, v245, 31
	v_readlane_b32 s48, v245, 32
	v_readlane_b32 s49, v245, 33
	v_readlane_b32 s50, v245, 34
	v_readlane_b32 s51, v245, 35
	v_readlane_b32 s38, v245, 6
	v_readlane_b32 s39, v245, 7
	v_readlane_b32 s40, v245, 8
	v_readlane_b32 s41, v245, 9
	v_readlane_b32 s42, v245, 10
	v_readlane_b32 s43, v245, 11
	v_mov_b32_e32 v118, v32
	v_ashrrev_i32_e32 v119, 31, v32
	v_lshlrev_b64 v[116:117], 12, v[118:119]
	v_lshl_add_u64 v[116:117], v[34:35], 0, v[116:117]
	global_load_dwordx4 v[38:41], v[116:117], off
	global_load_dwordx4 v[42:45], v[116:117], off offset:1024
	global_load_dwordx4 v[46:49], v[116:117], off offset:2048
	global_load_dwordx4 v[50:53], v[116:117], off offset:3072
	s_waitcnt vmcnt(0)
.LBB0_73:
	s_waitcnt vmcnt(8)
	v_mov_b32_e32 v100, v38
	v_mov_b32_e32 v101, v39
	v_mov_b32_e32 v102, v40
	v_mov_b32_e32 v103, v41
	v_mov_b32_e32 v104, v42
	v_mov_b32_e32 v105, v43
	v_mov_b32_e32 v106, v44
	v_mov_b32_e32 v107, v45
	v_mov_b32_e32 v108, v46
	v_mov_b32_e32 v109, v47
	v_mov_b32_e32 v110, v48
	v_mov_b32_e32 v111, v49
	v_mov_b32_e32 v112, v50
	v_mov_b32_e32 v113, v51
	v_mov_b32_e32 v114, v52
	v_mov_b32_e32 v115, v53
	v_ashrrev_i32_e32 v33, 31, v32
	v_lshlrev_b64 v[116:117], 12, v[32:33]
	v_lshl_add_u64 v[54:55], v[34:35], 0, v[116:117]
	s_load_dword s2, s[8:9], 0x0
	s_waitcnt lgkmcnt(0)
	v_lshl_add_u32 v118, s2, 2, v32
	v_cmp_lt_i32_e32 vcc, s24, v118
	s_nop 1
	v_cndmask_b32_e32 v118, v118, v32, vcc
	v_ashrrev_i32_e32 v119, 31, v118
	v_lshlrev_b64 v[116:117], 12, v[118:119]
	v_lshl_add_u64 v[116:117], v[34:35], 0, v[116:117]
	global_load_dwordx4 v[38:41], v[116:117], off
	global_load_dwordx4 v[42:45], v[116:117], off offset:1024
	global_load_dwordx4 v[46:49], v[116:117], off offset:2048
	global_load_dwordx4 v[50:53], v[116:117], off offset:3072
	s_nop 0
	s_nop 0
	v_mov_b32_e32 v56, v101
	v_mov_b32_e32 v57, v102
	v_mov_b32_e32 v58, v100
	v_mov_b32_e32 v59, v103
	v_pk_add_f32 v[56:57], v[56:57], v[58:59]
	v_mov_b32_e32 v58, v105
	v_mov_b32_e32 v59, v106
	v_mov_b32_e32 v60, v104
	v_mov_b32_e32 v61, v107
	v_pk_add_f32 v[58:59], v[58:59], v[60:61]
	v_add_f32_e32 v56, v56, v57
	v_pk_add_f32 v[58:59], v[58:59], v[58:59] op_sel_hi:[0,1]
	v_add_f32_e32 v57, 0, v56
	v_add_f32_e32 v61, v108, v109
	v_add_f32_e32 v63, v110, v111
	v_mov_b32_e32 v60, v112
	v_mov_b32_e32 v62, v113
	v_mov_b32_e32 v58, v114
	v_mov_b32_e32 v56, v115
	v_pk_add_f32 v[60:61], v[60:61], v[62:63]
	v_pk_add_f32 v[56:57], v[58:59], v[56:57]
	s_nop 0
	v_pk_add_f32 v[56:57], v[60:61], v[56:57]
	s_nop 0
	v_add_f32_e32 v56, v56, v57
	v_mbcnt_hi_u32_b32 v57, -1, v176
	v_and_b32_e32 v58, 64, v57
	v_add_u32_e32 v58, 64, v58
	v_xor_b32_e32 v59, 32, v57
	v_cmp_lt_i32_e32 vcc, v59, v58
	s_nop 1
	v_cndmask_b32_e32 v59, v57, v59, vcc
	v_lshlrev_b32_e32 v62, 2, v59
	ds_bpermute_b32 v59, v62, v56
	s_waitcnt lgkmcnt(0)
	v_add_f32_e32 v56, v56, v59
	v_xor_b32_e32 v59, 16, v57
	v_cmp_lt_i32_e32 vcc, v59, v58
	s_nop 1
	v_cndmask_b32_e32 v59, v57, v59, vcc
	v_lshlrev_b32_e32 v63, 2, v59
	ds_bpermute_b32 v59, v63, v56
	s_waitcnt lgkmcnt(0)
	v_add_f32_e32 v56, v56, v59
	v_xor_b32_e32 v59, 8, v57
	v_cmp_lt_i32_e32 vcc, v59, v58
	s_nop 1
	v_cndmask_b32_e32 v59, v57, v59, vcc
	v_lshlrev_b32_e32 v64, 2, v59
	ds_bpermute_b32 v59, v64, v56
	s_waitcnt lgkmcnt(0)
	v_add_f32_e32 v56, v56, v59
	v_xor_b32_e32 v59, 4, v57
	v_cmp_lt_i32_e32 vcc, v59, v58
	s_nop 1
	v_cndmask_b32_e32 v59, v57, v59, vcc
	v_lshlrev_b32_e32 v65, 2, v59
	ds_bpermute_b32 v59, v65, v56
	s_waitcnt lgkmcnt(0)
	v_add_f32_e32 v56, v56, v59
	v_xor_b32_e32 v59, 2, v57
	v_cmp_lt_i32_e32 vcc, v59, v58
	s_nop 1
	v_cndmask_b32_e32 v59, v57, v59, vcc
	v_lshlrev_b32_e32 v66, 2, v59
	ds_bpermute_b32 v59, v66, v56
	s_waitcnt lgkmcnt(0)
; DI float wave_sum(float v) { for (int o = 32; o >= 1; o >>= 1) v += __shfl_xor(v, o); return v; }
; DI void ln_phase(float* x32, bf16_t* xb, const float* g, const float* b) {
;     ...
;     for (int j = 0; j < 4; ++j) s += (v[j][0] + v[j][1]) + (v[j][2] + v[j][3]);
;     s = wave_sum(s); const float mu = s * (1.f / D_); float q = 0.f;
; #pragma unroll
;     for (int j = 0; j < 4; ++j) { v[j] -= mu; q += v[j][0] * v[j][0] + v[j][1] * v[j][1] + v[j][2] * v[j][2] + v[j][3] * v[j][3]; }
;     q = wave_sum(q); const float rs = rsqrtf(q * (1.f / D_) + 1e-5f);
	v_add_f32_e32 v56, v56, v59
	v_xor_b32_e32 v59, 1, v57
	v_cmp_lt_i32_e32 vcc, v59, v58
	s_nop 1
	v_cndmask_b32_e32 v57, v57, v59, vcc
	v_lshlrev_b32_e32 v67, 2, v57
	ds_bpermute_b32 v57, v67, v56
	s_waitcnt lgkmcnt(0)
	v_add_f32_e32 v60, v56, v57
	v_fmamk_f32 v101, v60, 0xba800000, v101
	v_fmamk_f32 v105, v60, 0xba800000, v105
	v_fmac_f32_e32 v100, 0xba800000, v60
	v_fmac_f32_e32 v104, 0xba800000, v60
	v_mov_b32_e32 v58, v101
	v_mov_b32_e32 v59, v105
	v_fmamk_f32 v102, v60, 0xba800000, v102
	v_fmamk_f32 v106, v60, 0xba800000, v106
	v_mov_b32_e32 v56, v100
	v_mov_b32_e32 v57, v104
	v_pk_mul_f32 v[58:59], v[58:59], v[58:59]
	v_fmamk_f32 v103, v60, 0xba800000, v103
	v_fmamk_f32 v107, v60, 0xba800000, v107
	v_pk_fma_f32 v[56:57], v[56:57], v[56:57], v[58:59]
	v_mov_b32_e32 v58, v102
	v_mov_b32_e32 v59, v106
	v_fmamk_f32 v109, v60, 0xba800000, v109
	v_fmamk_f32 v113, v60, 0xba800000, v113
	v_pk_fma_f32 v[56:57], v[58:59], v[58:59], v[56:57]
	v_mov_b32_e32 v58, v103
	v_mov_b32_e32 v59, v107
	v_fmamk_f32 v111, v60, 0xba800000, v111
	v_fmamk_f32 v110, v60, 0xba800000, v110
	v_fmac_f32_e32 v108, 0xba800000, v60
	v_fmamk_f32 v115, v60, 0xba800000, v115
	v_fmamk_f32 v114, v60, 0xba800000, v114
	v_fmac_f32_e32 v112, 0xba800000, v60
	v_mov_b32_e32 v60, v113
	v_mov_b32_e32 v61, v109
	v_pk_fma_f32 v[56:57], v[58:59], v[58:59], v[56:57]
	v_mov_b32_e32 v58, v112
	v_mov_b32_e32 v59, v108
	v_pk_mul_f32 v[60:61], v[60:61], v[60:61]
	v_add_f32_e32 v56, v56, v57
	v_pk_fma_f32 v[58:59], v[58:59], v[58:59], v[60:61]
	v_mov_b32_e32 v60, v114
	v_mov_b32_e32 v61, v110
	v_pk_fma_f32 v[58:59], v[60:61], v[60:61], v[58:59]
	v_mov_b32_e32 v60, v115
	v_mov_b32_e32 v61, v111
	v_pk_fma_f32 v[58:59], v[60:61], v[60:61], v[58:59]
	s_nop 0
	v_add_f32_e32 v56, v59, v56
	v_add_f32_e32 v56, v58, v56
	ds_bpermute_b32 v57, v62, v56
	v_lshlrev_b64 v[58:59], 11, v[32:33]
	v_lshl_add_u64 v[58:59], v[36:37], 0, v[58:59]
	s_waitcnt lgkmcnt(0)
	v_add_f32_e32 v56, v56, v57
	ds_bpermute_b32 v57, v63, v56
	s_waitcnt lgkmcnt(0)
	v_add_f32_e32 v56, v56, v57
	ds_bpermute_b32 v57, v64, v56
	s_waitcnt lgkmcnt(0)
	v_add_f32_e32 v56, v56, v57
	ds_bpermute_b32 v57, v65, v56
	s_waitcnt lgkmcnt(0)
	v_add_f32_e32 v56, v56, v57
	ds_bpermute_b32 v57, v66, v56
	s_waitcnt lgkmcnt(0)
	v_add_f32_e32 v56, v56, v57
	ds_bpermute_b32 v57, v67, v56
	s_waitcnt lgkmcnt(0)
; DI unsigned pack2(float a, float b) { return (unsigned)f2bf(a) | ((unsigned)f2bf(b) << 16); }
; DI float wave_sum(float v) { for (int o = 32; o >= 1; o >>= 1) v += __shfl_xor(v, o); return v; }
; DI void ln_phase(float* x32, bf16_t* xb, const float* g, const float* b) {
;     ...
;     q = wave_sum(q); const float rs = rsqrtf(q * (1.f / D_) + 1e-5f);
; #pragma unroll
;     for (int j = 0; j < 4; ++j) {
;       const int c = j * 256 + lane * 4;
;       float4 y; y.x = v[j][0] * rs * gg[j].x + bb[j].x; y.y = v[j][1] * rs * gg[j].y + bb[j].y; y.z = v[j][2] * rs * gg[j].z + bb[j].z; y.w = v[j][3] * rs * gg[j].w + bb[j].w;
;       *(float4*)(x32 + (size_t)row * D_ + c) = y;
;       uint2 pk; pk.x = pack2(y.x, y.y); pk.y = pack2(y.z, y.w); *(uint2*)(xb + (size_t)row * D_ + c) = pk;
;     }
;   }
	v_add_f32_e32 v56, v56, v57
	v_fmamk_f32 v56, v56, 0x3a800000, v171
	v_mul_f32_e32 v57, 0x4b800000, v56
	v_cmp_gt_f32_e32 vcc, s11, v56
	s_nop 1
	v_cndmask_b32_e32 v56, v56, v57, vcc
	v_rsq_f32_e32 v56, v56
	s_nop 0
	v_mul_f32_e32 v57, 0x45800000, v56
	v_cndmask_b32_e32 v56, v56, v57, vcc
	v_pk_mul_f32 v[100:101], v[100:101], v[56:57] op_sel_hi:[1,0]
	v_pk_mul_f32 v[102:103], v[102:103], v[56:57] op_sel_hi:[1,0]
	v_pk_fma_f32 v[100:101], v[0:1], v[100:101], v[8:9]
	v_pk_fma_f32 v[102:103], v[2:3], v[102:103], v[10:11]
	v_and_b32_sdwa v57, v100, v141 dst_sel:DWORD dst_unused:UNUSED_PAD src0_sel:WORD_1 src1_sel:DWORD
	v_and_b32_sdwa v33, v102, v141 dst_sel:DWORD dst_unused:UNUSED_PAD src0_sel:WORD_1 src1_sel:DWORD
	global_store_dwordx4 v[54:55], v[100:103], off
	v_add3_u32 v33, v102, v33, s17
	s_nop 0
	v_add3_u32 v100, v100, v57, s17
	v_and_b32_sdwa v102, v103, v141 dst_sel:DWORD dst_unused:UNUSED_PAD src0_sel:WORD_1 src1_sel:DWORD
	v_and_b32_sdwa v57, v101, v141 dst_sel:DWORD dst_unused:UNUSED_PAD src0_sel:WORD_1 src1_sel:DWORD
	v_add3_u32 v102, v103, v102, s17
	v_add3_u32 v101, v101, v57, s17
	v_and_b32_e32 v102, 0xffff0000, v102
	v_and_b32_e32 v103, 0xffff0000, v101
	v_or_b32_sdwa v101, v102, v33 dst_sel:DWORD dst_unused:UNUSED_PAD src0_sel:DWORD src1_sel:WORD_1
	v_or_b32_sdwa v100, v103, v100 dst_sel:DWORD dst_unused:UNUSED_PAD src0_sel:DWORD src1_sel:WORD_1
	global_store_dwordx2 v[58:59], v[100:101], off
	v_pk_mul_f32 v[100:101], v[104:105], v[56:57] op_sel_hi:[1,0]
	v_pk_mul_f32 v[102:103], v[106:107], v[56:57] op_sel_hi:[1,0]
	v_pk_fma_f32 v[100:101], v[4:5], v[100:101], v[12:13]
	v_pk_fma_f32 v[102:103], v[6:7], v[102:103], v[14:15]
	v_and_b32_sdwa v104, v100, v141 dst_sel:DWORD dst_unused:UNUSED_PAD src0_sel:WORD_1 src1_sel:DWORD
	v_and_b32_sdwa v33, v102, v141 dst_sel:DWORD dst_unused:UNUSED_PAD src0_sel:WORD_1 src1_sel:DWORD
	global_store_dwordx4 v[54:55], v[100:103], off offset:1024
	v_add3_u32 v33, v102, v33, s17
	s_nop 0
	v_add3_u32 v100, v100, v104, s17
	v_and_b32_sdwa v102, v103, v141 dst_sel:DWORD dst_unused:UNUSED_PAD src0_sel:WORD_1 src1_sel:DWORD
	v_and_b32_sdwa v104, v101, v141 dst_sel:DWORD dst_unused:UNUSED_PAD src0_sel:WORD_1 src1_sel:DWORD
	v_add3_u32 v102, v103, v102, s17
	v_add3_u32 v101, v101, v104, s17
	v_and_b32_e32 v102, 0xffff0000, v102
	v_and_b32_e32 v103, 0xffff0000, v101
	v_or_b32_sdwa v101, v102, v33 dst_sel:DWORD dst_unused:UNUSED_PAD src0_sel:DWORD src1_sel:WORD_1
	v_or_b32_sdwa v100, v103, v100 dst_sel:DWORD dst_unused:UNUSED_PAD src0_sel:DWORD src1_sel:WORD_1
	global_store_dwordx2 v[58:59], v[100:101], off offset:512
	v_pk_mul_f32 v[100:101], v[108:109], v[56:57] op_sel_hi:[1,0]
	v_pk_mul_f32 v[102:103], v[110:111], v[56:57] op_sel_hi:[1,0]
	v_pk_fma_f32 v[100:101], v[16:17], v[100:101], v[24:25]
	v_pk_fma_f32 v[102:103], v[18:19], v[102:103], v[26:27]
	v_and_b32_sdwa v104, v100, v141 dst_sel:DWORD dst_unused:UNUSED_PAD src0_sel:WORD_1 src1_sel:DWORD
	v_and_b32_sdwa v33, v102, v141 dst_sel:DWORD dst_unused:UNUSED_PAD src0_sel:WORD_1 src1_sel:DWORD
	global_store_dwordx4 v[54:55], v[100:103], off offset:2048
	v_add3_u32 v33, v102, v33, s17
	s_nop 0
	v_add3_u32 v100, v100, v104, s17
	v_and_b32_sdwa v102, v103, v141 dst_sel:DWORD dst_unused:UNUSED_PAD src0_sel:WORD_1 src1_sel:DWORD
	v_and_b32_sdwa v104, v101, v141 dst_sel:DWORD dst_unused:UNUSED_PAD src0_sel:WORD_1 src1_sel:DWORD
	v_add3_u32 v102, v103, v102, s17
	v_add3_u32 v101, v101, v104, s17
	v_and_b32_e32 v102, 0xffff0000, v102
	v_and_b32_e32 v103, 0xffff0000, v101
	v_or_b32_sdwa v101, v102, v33 dst_sel:DWORD dst_unused:UNUSED_PAD src0_sel:DWORD src1_sel:WORD_1
	v_or_b32_sdwa v100, v103, v100 dst_sel:DWORD dst_unused:UNUSED_PAD src0_sel:DWORD src1_sel:WORD_1
	global_store_dwordx2 v[58:59], v[100:101], off offset:1024
	v_pk_mul_f32 v[100:101], v[112:113], v[56:57] op_sel_hi:[1,0]
	v_pk_mul_f32 v[102:103], v[114:115], v[56:57] op_sel_hi:[1,0]
	v_pk_fma_f32 v[100:101], v[20:21], v[100:101], v[28:29]
	v_pk_fma_f32 v[102:103], v[22:23], v[102:103], v[30:31]
	v_and_b32_sdwa v104, v100, v141 dst_sel:DWORD dst_unused:UNUSED_PAD src0_sel:WORD_1 src1_sel:DWORD
	v_and_b32_sdwa v33, v102, v141 dst_sel:DWORD dst_unused:UNUSED_PAD src0_sel:WORD_1 src1_sel:DWORD
	global_store_dwordx4 v[54:55], v[100:103], off offset:3072
	v_add3_u32 v33, v102, v33, s17
	s_nop 0
	v_add3_u32 v100, v100, v104, s17
	v_and_b32_sdwa v102, v103, v141 dst_sel:DWORD dst_unused:UNUSED_PAD src0_sel:WORD_1 src1_sel:DWORD
	v_and_b32_sdwa v104, v101, v141 dst_sel:DWORD dst_unused:UNUSED_PAD src0_sel:WORD_1 src1_sel:DWORD
	v_add3_u32 v102, v103, v102, s17
	v_add3_u32 v101, v101, v104, s17
	v_and_b32_e32 v102, 0xffff0000, v102
	v_and_b32_e32 v103, 0xffff0000, v101
	v_or_b32_sdwa v101, v102, v33 dst_sel:DWORD dst_unused:UNUSED_PAD src0_sel:DWORD src1_sel:WORD_1
	v_or_b32_sdwa v100, v103, v100 dst_sel:DWORD dst_unused:UNUSED_PAD src0_sel:DWORD src1_sel:WORD_1
	global_store_dwordx2 v[58:59], v[100:101], off offset:1536
	s_load_dword s2, s[8:9], 0x0
	s_waitcnt lgkmcnt(0)
	v_lshl_add_u32 v32, s2, 2, v32
	v_cmp_lt_i32_e32 vcc, s24, v32
	s_or_b64 s[4:5], vcc, s[4:5]
	s_andn2_b64 exec, exec, s[4:5]
	s_cbranch_execnz .LBB0_73
.LBB0_74:
	s_or_b64 exec, exec, s[0:1]
	s_waitcnt vmcnt(0)
	v_readlane_b32 s0, v244, 5
	v_readlane_b32 s1, v244, 6
	s_andn2_b64 vcc, exec, s[0:1]
	s_cbranch_vccnz .LBB0_81
	v_readlane_b32 s0, v242, 20
	v_readlane_b32 s1, v242, 21
	v_readlane_b32 s36, v243, 59
	s_mov_b32 s4, s0
	s_mul_hi_i32 s1, s0, 0x1600000
	s_mul_i32 s0, s0, 0x1600000
	v_readlane_b32 s46, v242, 5
	v_readlane_b32 s47, v242, 6
	s_add_u32 s0, s46, s0
	v_readlane_b32 s48, v242, 7
	s_addc_u32 s1, s47, s1
	s_mul_hi_i32 s2, s4, 0xb00000
	s_mul_i32 s4, s4, 0xb00000
	v_readlane_b32 s49, v242, 8
	s_add_u32 s4, s48, s4
	v_readlane_b32 s6, v242, 15
	s_addc_u32 s5, s49, s2
	s_mov_b32 s2, s6
	v_readlane_b32 s37, v243, 60
	v_readlane_b32 s38, v243, 61
	v_readlane_b32 s39, v243, 62
	v_readlane_b32 s40, v243, 63
	v_readlane_b32 s41, v242, 0
	v_readlane_b32 s42, v242, 1
	v_readlane_b32 s43, v242, 2
	v_readlane_b32 s44, v242, 3
	v_readlane_b32 s45, v242, 4
	v_readlane_b32 s50, v242, 9
	v_readlane_b32 s51, v242, 10
	v_readlane_b32 s7, v242, 16
	s_branch .LBB0_77

; DI int tid_() { int t = __builtin_amdgcn_workitem_id_x(); asm volatile("" : "+v"(t)); return t; }
; DI f32x4 gldfv(const void* p) { f32x4 r; asm volatile("global_load_dwordx4 %0, %1, off" : "=v"(r) : "v"(p) : "memory"); return r; }
; DI void ln_phase(float* x32, bf16_t* xb, const float* g, const float* b) {
;   const int lane = tid_() & 63, wv = tid_() >> 6;
;   float4 gg[4], bb[4];
; #pragma unroll
;   for (int j = 0; j < 4; ++j) { gg[j] = *(const float4*)(g + j * 256 + lane * 4); bb[j] = *(const float4*)(b + j * 256 + lane * 4); }
;   for (int row = blockIdx.x * 4 + wv; row < T_; row += gridDim.x * 4) {
;     f32x4 v[4];
; #pragma unroll
;     for (int j = 0; j < 4; ++j) v[j] = gldfv(x32 + (size_t)row * D_ + j * 256 + lane * 4);
.LBB0_725:
	s_andn2_b64 vcc, exec, s[0:1]
	s_cbranch_vccnz .LBB0_750
	v_readlane_b32 s0, v242, 22
	s_cmp_gt_i32 s0, 0
	s_mov_b64 s[0:1], -1
	s_cbranch_scc0 .LBB0_748
	v_readlane_b32 s0, v242, 22
	s_cmp_gt_i32 s0, 1
	s_mov_b64 s[0:1], -1
	s_cbranch_scc0 .LBB0_732
	v_mov_b32_e32 v0, v170
	v_mov_b32_e32 v1, v170
	v_readlane_b32 s0, v245, 60
	v_ashrrev_i32_e32 v1, 6, v1
	s_nop 0
	v_add_u32_e32 v32, s0, v1
	s_movk_i32 s0, 0x4000
	v_cmp_gt_i32_e32 vcc, s0, v32
	s_and_saveexec_b64 s[0:1], vcc
	v_readlane_b32 s8, v245, 61
	v_readlane_b32 s9, v245, 62
	s_mov_b64 s[12:13], 0x400
	s_mov_b64 s[20:21], 0x800
	s_mov_b64 s[22:23], 0xc00
	s_mov_b32 s11, 0x800000
	s_movk_i32 s24, 0x3fff
	s_cbranch_execz .LBB0_731
	v_readlane_b32 s4, v242, 20
	v_readlane_b32 s5, v242, 21
	s_lshl_b32 s4, s4, 10
	s_ashr_i32 s5, s4, 31
	v_readlane_b32 s36, v243, 59
	s_lshl_b64 s[4:5], s[4:5], 2
	v_readlane_b32 s50, v242, 9
	v_readlane_b32 s37, v243, 60
	v_readlane_b32 s38, v243, 61
	v_readlane_b32 s39, v243, 62
	v_readlane_b32 s40, v243, 63
	v_readlane_b32 s41, v242, 0
	v_readlane_b32 s42, v242, 1
	v_readlane_b32 s43, v242, 2
	v_readlane_b32 s44, v242, 3
	v_readlane_b32 s45, v242, 4
	v_readlane_b32 s46, v242, 5
	v_readlane_b32 s47, v242, 6
	v_readlane_b32 s48, v242, 7
	v_readlane_b32 s49, v242, 8
	v_readlane_b32 s51, v242, 10
	s_add_u32 s6, s50, s4
	v_lshlrev_b32_e32 v0, 2, v0
	s_addc_u32 s7, s51, s5
	v_readlane_b32 s36, v245, 20
	v_and_b32_e32 v33, 0xfc, v0
	v_readlane_b32 s37, v245, 21
	s_add_u32 s4, s36, s4
	v_lshlrev_b32_e32 v142, 2, v33
	s_addc_u32 s5, s37, s5
	global_load_dwordx4 v[0:3], v142, s[6:7]
	global_load_dwordx4 v[4:7], v142, s[6:7] offset:1024
	global_load_dwordx4 v[8:11], v142, s[4:5]
	global_load_dwordx4 v[12:15], v142, s[4:5] offset:1024
	global_load_dwordx4 v[16:19], v142, s[6:7] offset:2048
	global_load_dwordx4 v[20:23], v142, s[6:7] offset:3072
	global_load_dwordx4 v[24:27], v142, s[4:5] offset:2048
	global_load_dwordx4 v[28:31], v142, s[4:5] offset:3072
	v_readlane_b32 s38, v245, 22
	v_readlane_b32 s39, v245, 23
	v_readlane_b32 s40, v245, 24
	v_readlane_b32 s41, v245, 25
	v_readlane_b32 s42, v245, 26
	v_readlane_b32 s43, v245, 27
	v_readlane_b32 s36, v245, 4
	v_readlane_b32 s37, v245, 5
	v_readlane_b32 s4, v245, 52
	v_readlane_b32 s5, v245, 53
	v_lshl_add_u64 v[34:35], s[36:37], 0, v[142:143]
	v_lshlrev_b32_e32 v142, 1, v33
	v_lshl_add_u64 v[36:37], s[4:5], 0, v[142:143]
	s_mov_b64 s[4:5], 0
	v_readlane_b32 s44, v245, 28
	v_readlane_b32 s45, v245, 29
	v_readlane_b32 s46, v245, 30
	v_readlane_b32 s47, v245, 31
	v_readlane_b32 s48, v245, 32
	v_readlane_b32 s49, v245, 33
	v_readlane_b32 s50, v245, 34
	v_readlane_b32 s51, v245, 35
	v_readlane_b32 s38, v245, 6
	v_readlane_b32 s39, v245, 7
	v_readlane_b32 s40, v245, 8
	v_readlane_b32 s41, v245, 9
	v_readlane_b32 s42, v245, 10
	v_readlane_b32 s43, v245, 11
	v_mov_b32_e32 v118, v32
	v_ashrrev_i32_e32 v119, 31, v32
	v_lshlrev_b64 v[116:117], 12, v[118:119]
	v_lshl_add_u64 v[116:117], v[34:35], 0, v[116:117]
	global_load_dwordx4 v[38:41], v[116:117], off
	global_load_dwordx4 v[42:45], v[116:117], off offset:1024
	global_load_dwordx4 v[46:49], v[116:117], off offset:2048
	global_load_dwordx4 v[50:53], v[116:117], off offset:3072
	s_waitcnt vmcnt(0)

; DI unsigned pack2(float a, float b) { return (unsigned)f2bf(a) | ((unsigned)f2bf(b) << 16); }
; DI float wave_sum(float v) { for (int o = 32; o >= 1; o >>= 1) v += __shfl_xor(v, o); return v; }
; DI f32x4 gldfv(const void* p) { f32x4 r; asm volatile("global_load_dwordx4 %0, %1, off" : "=v"(r) : "v"(p) : "memory"); return r; }
; DI void ln_phase(float* x32, bf16_t* xb, const float* g, const float* b) {
;     ...
;   for (int row = blockIdx.x * 4 + wv; row < T_; row += gridDim.x * 4) {
;     f32x4 v[4];
; #pragma unroll
;     for (int j = 0; j < 4; ++j) v[j] = gldfv(x32 + (size_t)row * D_ + j * 256 + lane * 4);
;     asm volatile("s_waitcnt vmcnt(0)" : "+v"(v[0]), "+v"(v[1]), "+v"(v[2]), "+v"(v[3]) :: "memory");
;     float s = 0.f;
; #pragma unroll
;     for (int j = 0; j < 4; ++j) s += (v[j][0] + v[j][1]) + (v[j][2] + v[j][3]);
;     s = wave_sum(s); const float mu = s * (1.f / D_); float q = 0.f;
; #pragma unroll
;     for (int j = 0; j < 4; ++j) { v[j] -= mu; q += v[j][0] * v[j][0] + v[j][1] * v[j][1] + v[j][2] * v[j][2] + v[j][3] * v[j][3]; }
;     q = wave_sum(q); const float rs = rsqrtf(q * (1.f / D_) + 1e-5f);
; #pragma unroll
;     for (int j = 0; j < 4; ++j) {
;       const int c = j * 256 + lane * 4;
;       float4 y; y.x = v[j][0] * rs * gg[j].x + bb[j].x; y.y = v[j][1] * rs * gg[j].y + bb[j].y; y.z = v[j][2] * rs * gg[j].z + bb[j].z; y.w = v[j][3] * rs * gg[j].w + bb[j].w;
;       *(float4*)(x32 + (size_t)row * D_ + c) = y;
;       uint2 pk; pk.x = pack2(y.x, y.y); pk.y = pack2(y.z, y.w); *(uint2*)(xb + (size_t)row * D_ + c) = pk;
;     }
;   }
.LBB0_731:
	s_or_b64 exec, exec, s[0:1]
	s_waitcnt vmcnt(0)
	s_mov_b64 s[0:1], 0
